# branch gate epilogue: specialised copy for non-last segments drops 128 wave-uniform selects per segment
# speedup vs baseline: 1.0060x; 1.0060x over previous
.LBB0_114:
	s_lshl_b32 s22, s52, 4
	s_lshl_b32 s28, s26, 5
	s_add_i32 s22, s22, s20
	s_ashr_i32 s29, s28, 31
	s_lshl_b32 s27, s55, 3
	s_ashr_i32 s23, s22, 31
	s_ashr_i32 s30, s27, 31
	s_or_b64 s[28:29], s[28:29], s[0:1]
	s_add_u32 s28, s28, s27
	s_addc_u32 s29, s29, s30
	s_lshl_b64 s[22:23], s[22:23], 17
	s_lshl_b64 s[28:29], s[28:29], 10
	s_add_u32 s22, s78, s22
	s_addc_u32 s23, s79, s23
	s_add_u32 s22, s22, s28
	s_addc_u32 s23, s23, s29
	v_mov_b32_e32 v100, v245
	s_cmp_eq_u32 s26, 3
	s_cselect_b64 s[36:37], -1, 0
	v_ashrrev_i32_e32 v101, 31, v100
	v_lshl_add_u64 v[208:209], v[100:101], 4, s[22:23]
	s_and_b64 s[28:29], s[36:37], exec
	global_load_dwordx4 v[198:201], v[208:209], off
	s_cselect_b32 s27, 0, 0x800
	s_lshl_b32 s88, s27, 4
	v_lshl_add_u64 v[100:101], v[208:209], 0, s[88:89]
	global_load_dwordx4 v[202:205], v[100:101], off
	s_mov_b64 s[22:23], 0x20000
	v_lshl_add_u64 v[100:101], v[208:209], 0, s[22:23]
	s_mov_b32 s22, 0x21000
	v_add_co_u32_e32 v102, vcc, s22, v208
	v_lshl_add_u64 v[100:101], v[100:101], 0, s[88:89]
	s_nop 0
	v_addc_co_u32_e32 v103, vcc, 0, v209, vcc
	s_mov_b64 s[22:23], 0x40000
	global_load_dwordx4 v[180:183], v[102:103], off offset:-4096
	global_load_dwordx4 v[176:179], v[100:101], off
	v_lshl_add_u64 v[100:101], v[208:209], 0, s[22:23]
	s_mov_b32 s22, 0x41000
	v_lshl_add_u64 v[100:101], v[100:101], 0, s[88:89]
	v_add_co_u32_e32 v104, vcc, s22, v208
	global_load_dwordx4 v[172:175], v[100:101], off
	global_load_dwordx4 v[140:143], v[102:103], off
	v_lshl_add_u64 v[100:101], v[208:209], 0, s[82:83]
	v_addc_co_u32_e32 v105, vcc, 0, v209, vcc
	v_lshl_add_u64 v[100:101], v[100:101], 0, s[88:89]
	global_load_dwordx4 v[168:171], v[104:105], off offset:-4096
	global_load_dwordx4 v[160:163], v[100:101], off
	s_mov_b32 s22, 0x61000
	v_lshl_add_u64 v[100:101], v[208:209], 0, s[94:95]
	v_add_co_u32_e32 v106, vcc, s22, v208
	v_lshl_add_u64 v[100:101], v[100:101], 0, s[88:89]
	s_mov_b64 s[22:23], 0x21000
	global_load_dwordx4 v[152:155], v[100:101], off
	global_load_dwordx4 v[120:123], v[104:105], off
	v_lshl_add_u64 v[100:101], v[208:209], 0, s[22:23]
	v_addc_co_u32_e32 v107, vcc, 0, v209, vcc
	s_movk_i32 s4, 0x1000
	v_lshl_add_u64 v[100:101], v[100:101], 0, s[88:89]
	s_mov_b64 s[22:23], 0x41000
	global_load_dwordx4 v[164:167], v[106:107], off offset:-4096
	global_load_dwordx4 v[132:135], v[100:101], off
	v_add_co_u32_e32 v116, vcc, s4, v208
	v_lshl_add_u64 v[100:101], v[208:209], 0, s[22:23]
	s_nop 0
	v_addc_co_u32_e32 v117, vcc, 0, v209, vcc
	v_lshl_add_u64 v[100:101], v[100:101], 0, s[88:89]
	s_mov_b64 s[22:23], 0x61000
	global_load_dwordx4 v[156:159], v[116:117], off
	s_movk_i32 s33, 0x3fff
	global_load_dwordx4 v[116:119], v[100:101], off
	s_cmp_lg_u32 s26, 3
	global_load_dwordx4 v[104:107], v[106:107], off
	v_lshl_add_u64 v[100:101], v[208:209], 0, s[22:23]
	v_lshl_add_u64 v[100:101], v[100:101], 0, s[88:89]
	global_load_dwordx4 v[100:103], v[100:101], off
	v_lshl_add_u32 v216, s52, 8, v242
	s_cbranch_scc1 .Lbrn_start
	s_waitcnt vmcnt(14)
	v_lshlrev_b32_e32 v206, 16, v198
	v_and_b32_e32 v207, 0xffff0000, v198
	v_rcp_f32_e32 v206, v206
	v_rcp_f32_e32 v207, v207
	v_lshlrev_b32_e32 v210, 16, v199
	v_and_b32_e32 v211, 0xffff0000, v199
	v_lshlrev_b32_e32 v198, 16, v202
	v_and_b32_e32 v199, 0xffff0000, v202
	v_pk_mul_f32 v[198:199], v[206:207], v[198:199]
	v_lshlrev_b32_e32 v212, 16, v200
	v_cndmask_b32_e64 v199, v199, v207, s[36:37]
	v_cndmask_b32_e64 v198, v198, v206, s[36:37]
	v_pk_mul_f32 v[198:199], v[148:149], v[198:199]
	v_rcp_f32_e32 v148, v210
	v_rcp_f32_e32 v149, v211
	v_and_b32_e32 v213, 0xffff0000, v200
	v_lshlrev_b32_e32 v214, 16, v201
	v_and_b32_e32 v215, 0xffff0000, v201
	v_lshlrev_b32_e32 v200, 16, v203
	v_and_b32_e32 v201, 0xffff0000, v203
	v_pk_mul_f32 v[200:201], v[148:149], v[200:201]
	v_lshlrev_b32_e32 v202, 16, v204
	v_cndmask_b32_e64 v149, v201, v149, s[36:37]
	v_cndmask_b32_e64 v148, v200, v148, s[36:37]
	v_pk_mul_f32 v[200:201], v[150:151], v[148:149]
	v_rcp_f32_e32 v148, v212
	v_rcp_f32_e32 v149, v213
	v_and_b32_e32 v203, 0xffff0000, v204
	v_lshlrev_b32_e32 v204, 16, v205
	v_and_b32_e32 v205, 0xffff0000, v205
	v_pk_mul_f32 v[150:151], v[148:149], v[202:203]
	v_lshl_or_b32 v206, s55, 8, v192
	v_cndmask_b32_e64 v149, v151, v149, s[36:37]
	v_cndmask_b32_e64 v148, v150, v148, s[36:37]
	v_pk_mul_f32 v[202:203], v[144:145], v[148:149]
	v_rcp_f32_e32 v144, v214
	v_rcp_f32_e32 v145, v215
	s_nop 0
	v_pk_mul_f32 v[148:149], v[144:145], v[204:205]
	s_nop 0
	v_cndmask_b32_e64 v145, v149, v145, s[36:37]
	v_cndmask_b32_e64 v144, v148, v144, s[36:37]
	v_pk_mul_f32 v[204:205], v[146:147], v[144:145]
	s_cbranch_scc1 .LBB0_116
	v_ashrrev_i32_e32 v217, 31, v216
	s_nop 1
	v_lshlrev_b64 v[148:149], 11, v[216:217]
	v_readlane_b32 s6, v253, 18
	v_readlane_b32 s7, v253, 19
	v_ashrrev_i32_e32 v207, 31, v206
	v_cvt_pk_bf16_f32 v144, v198, v199
	v_cvt_pk_bf16_f32 v145, v200, v201
	v_cvt_pk_bf16_f32 v146, v202, v203
	v_cvt_pk_bf16_f32 v147, v204, v205
	s_nop 0
	v_lshl_add_u64 v[148:149], s[6:7], 0, v[148:149]
	v_lshl_add_u64 v[148:149], v[206:207], 1, v[148:149]
	s_nop 1
	global_store_dwordx4 v[148:149], v[144:147], off

.Lbrn_start:
	s_waitcnt vmcnt(14)
	v_lshlrev_b32_e32 v206, 16, v198
	v_and_b32_e32 v207, 0xffff0000, v198
	v_rcp_f32_e32 v206, v206
	v_rcp_f32_e32 v207, v207
	v_lshlrev_b32_e32 v210, 16, v199
	v_and_b32_e32 v211, 0xffff0000, v199
	v_lshlrev_b32_e32 v198, 16, v202
	v_and_b32_e32 v199, 0xffff0000, v202
	v_pk_mul_f32 v[198:199], v[206:207], v[198:199]
	v_lshlrev_b32_e32 v212, 16, v200
	v_pk_mul_f32 v[198:199], v[148:149], v[198:199]
	v_rcp_f32_e32 v148, v210
	v_rcp_f32_e32 v149, v211
	v_and_b32_e32 v213, 0xffff0000, v200
	v_lshlrev_b32_e32 v214, 16, v201
	v_and_b32_e32 v215, 0xffff0000, v201
	v_lshlrev_b32_e32 v200, 16, v203
	v_and_b32_e32 v201, 0xffff0000, v203
	v_pk_mul_f32 v[200:201], v[148:149], v[200:201]
	v_lshlrev_b32_e32 v202, 16, v204
	v_pk_mul_f32 v[200:201], v[150:151], v[200:201]
	v_rcp_f32_e32 v148, v212
	v_rcp_f32_e32 v149, v213
	v_and_b32_e32 v203, 0xffff0000, v204
	v_lshlrev_b32_e32 v204, 16, v205
	v_and_b32_e32 v205, 0xffff0000, v205
	v_pk_mul_f32 v[150:151], v[148:149], v[202:203]
	v_lshl_or_b32 v206, s55, 8, v192
	v_pk_mul_f32 v[202:203], v[144:145], v[150:151]
	v_rcp_f32_e32 v144, v214
	v_rcp_f32_e32 v145, v215
	s_nop 0
	v_pk_mul_f32 v[148:149], v[144:145], v[204:205]
	s_nop 0
	v_pk_mul_f32 v[204:205], v[146:147], v[148:149]
	s_cbranch_scc1 .Lbrn_116
	v_ashrrev_i32_e32 v217, 31, v216
	s_nop 1
	v_lshlrev_b64 v[148:149], 11, v[216:217]
	v_readlane_b32 s6, v253, 18
	v_readlane_b32 s7, v253, 19
	v_ashrrev_i32_e32 v207, 31, v206
	v_cvt_pk_bf16_f32 v144, v198, v199
	v_cvt_pk_bf16_f32 v145, v200, v201
	v_cvt_pk_bf16_f32 v146, v202, v203
	v_cvt_pk_bf16_f32 v147, v204, v205
	s_nop 0
	v_lshl_add_u64 v[148:149], s[6:7], 0, v[148:149]
	v_lshl_add_u64 v[148:149], v[206:207], 1, v[148:149]
	s_nop 1
	global_store_dwordx4 v[148:149], v[144:147], off
.Lbrn_116:
	s_waitcnt vmcnt(12)
	v_lshlrev_b32_e32 v207, 16, v180
	v_and_b32_e32 v180, 0xffff0000, v180
	v_lshlrev_b32_e32 v144, 16, v176
	v_and_b32_e32 v145, 0xffff0000, v176
	v_lshlrev_b32_e32 v146, 16, v177
	v_and_b32_e32 v147, 0xffff0000, v177
	v_rcp_f32_e32 v176, v207
	v_rcp_f32_e32 v177, v180
	v_lshlrev_b32_e32 v210, 16, v181
	v_and_b32_e32 v181, 0xffff0000, v181
	v_lshlrev_b32_e32 v211, 16, v182
	v_pk_mul_f32 v[144:145], v[176:177], v[144:145]
	v_and_b32_e32 v182, 0xffff0000, v182
	v_pk_mul_f32 v[176:177], v[136:137], v[144:145]
	v_rcp_f32_e32 v136, v210
	v_rcp_f32_e32 v137, v181
	v_lshlrev_b32_e32 v148, 16, v178
	v_and_b32_e32 v149, 0xffff0000, v178
	v_lshlrev_b32_e32 v150, 16, v179
	v_pk_mul_f32 v[144:145], v[136:137], v[146:147]
	v_and_b32_e32 v151, 0xffff0000, v179
	v_pk_mul_f32 v[178:179], v[138:139], v[144:145]
	v_rcp_f32_e32 v136, v211
	v_rcp_f32_e32 v137, v182
	v_lshlrev_b32_e32 v212, 16, v183
	v_and_b32_e32 v183, 0xffff0000, v183
	s_andn2_b64 vcc, exec, s[36:37]
	v_pk_mul_f32 v[138:139], v[136:137], v[148:149]
	s_nop 0
	v_pk_mul_f32 v[180:181], v[128:129], v[138:139]
	v_rcp_f32_e32 v128, v212
	v_rcp_f32_e32 v129, v183
	s_nop 0
	v_pk_mul_f32 v[136:137], v[128:129], v[150:151]
	s_nop 0
	v_pk_mul_f32 v[182:183], v[130:131], v[136:137]
	v_cndmask_b32_e64 v128, 0, 1, s[36:37]
	v_cmp_ne_u32_e64 s[38:39], 1, v128
	v_or_b32_e32 v128, 16, v242
	v_lshl_add_u32 v214, s52, 8, v128
	s_cbranch_vccnz .Lbrn_118
	v_ashrrev_i32_e32 v215, 31, v214
	s_nop 1
	v_lshlrev_b64 v[136:137], 11, v[214:215]
	v_readlane_b32 s6, v253, 18
	v_readlane_b32 s7, v253, 19
	v_ashrrev_i32_e32 v207, 31, v206
	v_cvt_pk_bf16_f32 v128, v176, v177
	v_cvt_pk_bf16_f32 v129, v178, v179
	v_cvt_pk_bf16_f32 v130, v180, v181
	v_cvt_pk_bf16_f32 v131, v182, v183
	s_nop 0
	v_lshl_add_u64 v[136:137], s[6:7], 0, v[136:137]
	v_lshl_add_u64 v[136:137], v[206:207], 1, v[136:137]
	s_nop 1
	global_store_dwordx4 v[136:137], v[128:131], off
.Lbrn_118:
	s_waitcnt vmcnt(9)
	v_lshlrev_b32_e32 v144, 16, v168
	v_and_b32_e32 v145, 0xffff0000, v168
	v_rcp_f32_e32 v144, v144
	v_rcp_f32_e32 v145, v145
	v_lshlrev_b32_e32 v128, 16, v172
	v_and_b32_e32 v129, 0xffff0000, v172
	v_lshlrev_b32_e32 v146, 16, v169
	v_pk_mul_f32 v[128:129], v[144:145], v[128:129]
	v_and_b32_e32 v147, 0xffff0000, v169
	v_pk_mul_f32 v[168:169], v[124:125], v[128:129]
	v_rcp_f32_e32 v124, v146
	v_rcp_f32_e32 v125, v147
	v_lshlrev_b32_e32 v130, 16, v173
	v_and_b32_e32 v131, 0xffff0000, v173
	v_lshlrev_b32_e32 v148, 16, v170
	v_pk_mul_f32 v[128:129], v[124:125], v[130:131]
	v_and_b32_e32 v149, 0xffff0000, v170
	v_lshlrev_b32_e32 v150, 16, v171
	v_and_b32_e32 v151, 0xffff0000, v171
	v_pk_mul_f32 v[170:171], v[126:127], v[128:129]
	v_rcp_f32_e32 v124, v148
	v_rcp_f32_e32 v125, v149
	v_lshlrev_b32_e32 v136, 16, v174
	v_and_b32_e32 v137, 0xffff0000, v174
	v_lshlrev_b32_e32 v138, 16, v175
	v_pk_mul_f32 v[126:127], v[124:125], v[136:137]
	v_and_b32_e32 v139, 0xffff0000, v175
	v_pk_mul_f32 v[172:173], v[112:113], v[126:127]
	v_rcp_f32_e32 v112, v150
	v_rcp_f32_e32 v113, v151
	s_and_b64 vcc, exec, s[38:39]
	v_pk_mul_f32 v[124:125], v[112:113], v[138:139]
	s_nop 0
	v_pk_mul_f32 v[174:175], v[114:115], v[124:125]
	v_or_b32_e32 v112, 32, v242
	v_lshl_add_u32 v212, s52, 8, v112
	s_cbranch_vccnz .Lbrn_120
	v_ashrrev_i32_e32 v213, 31, v212
	s_nop 1
	v_lshlrev_b64 v[124:125], 11, v[212:213]
	v_readlane_b32 s6, v253, 18
	v_readlane_b32 s7, v253, 19
	v_ashrrev_i32_e32 v207, 31, v206
	v_cvt_pk_bf16_f32 v112, v168, v169
	v_cvt_pk_bf16_f32 v113, v170, v171
	v_cvt_pk_bf16_f32 v114, v172, v173
	v_cvt_pk_bf16_f32 v115, v174, v175
	s_nop 0
	v_lshl_add_u64 v[124:125], s[6:7], 0, v[124:125]
	v_lshl_add_u64 v[124:125], v[206:207], 1, v[124:125]
	s_nop 1
	global_store_dwordx4 v[124:125], v[112:115], off
.Lbrn_120:
	s_waitcnt vmcnt(5)
	v_lshlrev_b32_e32 v128, 16, v164
	v_and_b32_e32 v129, 0xffff0000, v164
	v_rcp_f32_e32 v128, v128
	v_rcp_f32_e32 v129, v129
	v_lshlrev_b32_e32 v112, 16, v160
	v_and_b32_e32 v113, 0xffff0000, v160
	v_lshlrev_b32_e32 v130, 16, v165
	v_pk_mul_f32 v[112:113], v[128:129], v[112:113]
	v_and_b32_e32 v131, 0xffff0000, v165
	v_lshlrev_b32_e32 v114, 16, v161
	v_and_b32_e32 v115, 0xffff0000, v161
	v_pk_mul_f32 v[160:161], v[108:109], v[112:113]
	v_rcp_f32_e32 v108, v130
	v_rcp_f32_e32 v109, v131
	v_lshlrev_b32_e32 v136, 16, v166
	v_and_b32_e32 v137, 0xffff0000, v166
	v_lshlrev_b32_e32 v124, 16, v162
	v_pk_mul_f32 v[112:113], v[108:109], v[114:115]
	v_and_b32_e32 v125, 0xffff0000, v162
	v_lshlrev_b32_e32 v126, 16, v163
	v_and_b32_e32 v127, 0xffff0000, v163
	v_pk_mul_f32 v[162:163], v[110:111], v[112:113]
	v_rcp_f32_e32 v108, v136
	v_rcp_f32_e32 v109, v137
	v_lshlrev_b32_e32 v138, 16, v167
	v_and_b32_e32 v139, 0xffff0000, v167
	s_and_b64 vcc, exec, s[38:39]
	v_pk_mul_f32 v[110:111], v[108:109], v[124:125]
	v_lshl_add_u32 v210, s52, 8, v246
	v_pk_mul_f32 v[164:165], v[96:97], v[110:111]
	v_rcp_f32_e32 v96, v138
	v_rcp_f32_e32 v97, v139
	s_nop 0
	v_pk_mul_f32 v[108:109], v[96:97], v[126:127]
	s_nop 0
	v_pk_mul_f32 v[166:167], v[98:99], v[108:109]
	s_cbranch_vccnz .Lbrn_122
	v_ashrrev_i32_e32 v211, 31, v210
	s_nop 1
	v_lshlrev_b64 v[108:109], 11, v[210:211]
	v_readlane_b32 s6, v253, 18
	v_readlane_b32 s7, v253, 19
	v_ashrrev_i32_e32 v207, 31, v206
	v_cvt_pk_bf16_f32 v96, v160, v161
	v_cvt_pk_bf16_f32 v97, v162, v163
	v_cvt_pk_bf16_f32 v98, v164, v165
	v_cvt_pk_bf16_f32 v99, v166, v167
	s_nop 0
	v_lshl_add_u64 v[108:109], s[6:7], 0, v[108:109]
	v_lshl_add_u64 v[108:109], v[206:207], 1, v[108:109]
	s_nop 1
	global_store_dwordx4 v[108:109], v[96:99], off
.Lbrn_122:
	s_mov_b64 s[22:23], 0x100000
	s_nop 0
	v_lshl_add_u64 v[96:97], v[208:209], 0, s[22:23]
	v_add_co_u32_e32 v98, vcc, 0x100000, v208
	v_lshl_add_u64 v[96:97], v[96:97], 0, s[88:89]
	s_nop 0
	v_addc_co_u32_e32 v99, vcc, 0, v209, vcc
	s_mov_b64 s[22:23], 0x120000
	global_load_dwordx4 v[144:147], v[98:99], off
	global_load_dwordx4 v[148:151], v[96:97], off
	v_lshl_add_u64 v[96:97], v[208:209], 0, s[22:23]
	v_add_co_u32_e32 v98, vcc, 0x120000, v208
	v_lshl_add_u64 v[96:97], v[96:97], 0, s[88:89]
	s_nop 0
	v_addc_co_u32_e32 v99, vcc, 0, v209, vcc
	s_mov_b64 s[22:23], 0x140000
	global_load_dwordx4 v[128:131], v[98:99], off
	global_load_dwordx4 v[136:139], v[96:97], off
	v_lshl_add_u64 v[96:97], v[208:209], 0, s[22:23]
	v_add_co_u32_e32 v98, vcc, 0x140000, v208
	v_lshl_add_u64 v[96:97], v[96:97], 0, s[88:89]
	s_nop 0
	v_addc_co_u32_e32 v99, vcc, 0, v209, vcc
	s_mov_b64 s[22:23], 0x160000
	global_load_dwordx4 v[112:115], v[98:99], off
	global_load_dwordx4 v[124:127], v[96:97], off
	v_lshl_add_u64 v[108:109], v[208:209], 0, s[22:23]
	v_add_co_u32_e32 v96, vcc, 0x160000, v208
	v_lshl_add_u64 v[108:109], v[108:109], 0, s[88:89]
	s_nop 0
	v_addc_co_u32_e32 v97, vcc, 0, v209, vcc
	global_load_dwordx4 v[96:99], v[96:97], off
	s_waitcnt vmcnt(10)
	v_lshlrev_b32_e32 v207, 16, v156
	global_load_dwordx4 v[108:111], v[108:109], off
	v_and_b32_e32 v211, 0xffff0000, v156
	v_lshlrev_b32_e32 v213, 16, v157
	v_and_b32_e32 v215, 0xffff0000, v157
	v_lshlrev_b32_e32 v217, 16, v158
	v_and_b32_e32 v251, 0xffff0000, v158
	v_lshlrev_b32_e32 v252, 16, v159
	v_and_b32_e32 v234, 0xffff0000, v159
	v_lshlrev_b32_e32 v156, 16, v152
	v_and_b32_e32 v157, 0xffff0000, v152
	v_lshlrev_b32_e32 v158, 16, v153
	v_and_b32_e32 v159, 0xffff0000, v153
	v_rcp_f32_e32 v152, v207
	v_rcp_f32_e32 v153, v211
	v_lshlrev_b32_e32 v230, 16, v154
	v_and_b32_e32 v231, 0xffff0000, v154
	v_lshlrev_b32_e32 v232, 16, v155
	v_and_b32_e32 v233, 0xffff0000, v155
	v_pk_mul_f32 v[154:155], v[152:153], v[156:157]
	s_and_b64 vcc, exec, s[38:39]
	v_pk_mul_f32 v[152:153], v[92:93], v[154:155]
	v_rcp_f32_e32 v92, v213
	v_rcp_f32_e32 v93, v215
	s_nop 0
	v_pk_mul_f32 v[154:155], v[92:93], v[158:159]
	s_nop 0
	v_pk_mul_f32 v[154:155], v[94:95], v[154:155]
	v_rcp_f32_e32 v92, v217
	v_rcp_f32_e32 v93, v251
	s_nop 0
	v_pk_mul_f32 v[94:95], v[92:93], v[230:231]
	s_nop 0
	v_pk_mul_f32 v[156:157], v[88:89], v[94:95]
	v_rcp_f32_e32 v88, v252
	v_rcp_f32_e32 v89, v234
	s_nop 0
	v_pk_mul_f32 v[92:93], v[88:89], v[232:233]
	s_nop 0
	v_pk_mul_f32 v[158:159], v[90:91], v[92:93]
	s_cbranch_vccnz .Lbrn_124
	s_lshl_b32 s22, s55, 8
	v_ashrrev_i32_e32 v217, 31, v216
	s_nop 1
	v_lshlrev_b64 v[92:93], 11, v[216:217]
	v_readlane_b32 s6, v253, 18
	v_readlane_b32 s7, v253, 19
	s_ashr_i32 s23, s22, 31
	v_mov_b32_e32 v95, s23
	v_lshl_add_u64 v[92:93], s[6:7], 0, v[92:93]
	v_or_b32_e32 v94, s22, v192
	v_lshl_add_u64 v[92:93], v[94:95], 1, v[92:93]
	v_cvt_pk_bf16_f32 v88, v152, v153
	v_cvt_pk_bf16_f32 v89, v154, v155
	v_cvt_pk_bf16_f32 v90, v156, v157
	v_cvt_pk_bf16_f32 v91, v158, v159
	s_nop 1
	global_store_dwordx4 v[92:93], v[88:91], off offset:256
.Lbrn_124:
	v_lshlrev_b32_e32 v207, 16, v140
	v_and_b32_e32 v140, 0xffff0000, v140
	v_lshlrev_b32_e32 v88, 16, v132
	v_and_b32_e32 v89, 0xffff0000, v132
	v_lshlrev_b32_e32 v90, 16, v133
	v_and_b32_e32 v91, 0xffff0000, v133
	v_rcp_f32_e32 v132, v207
	v_rcp_f32_e32 v133, v140
	v_lshlrev_b32_e32 v211, 16, v141
	v_and_b32_e32 v141, 0xffff0000, v141
	v_lshlrev_b32_e32 v213, 16, v142
	v_pk_mul_f32 v[88:89], v[132:133], v[88:89]
	v_and_b32_e32 v142, 0xffff0000, v142
	v_pk_mul_f32 v[132:133], v[84:85], v[88:89]
	v_rcp_f32_e32 v84, v211
	v_rcp_f32_e32 v85, v141
	v_lshlrev_b32_e32 v92, 16, v134
	v_and_b32_e32 v93, 0xffff0000, v134
	v_lshlrev_b32_e32 v94, 16, v135
	v_pk_mul_f32 v[88:89], v[84:85], v[90:91]
	v_and_b32_e32 v95, 0xffff0000, v135
	v_pk_mul_f32 v[134:135], v[86:87], v[88:89]
	v_rcp_f32_e32 v84, v213
	v_rcp_f32_e32 v85, v142
	v_lshlrev_b32_e32 v215, 16, v143
	v_and_b32_e32 v143, 0xffff0000, v143
	s_and_b64 vcc, exec, s[38:39]
	v_pk_mul_f32 v[86:87], v[84:85], v[92:93]
	s_nop 0
	v_pk_mul_f32 v[140:141], v[80:81], v[86:87]
	v_rcp_f32_e32 v80, v215
	v_rcp_f32_e32 v81, v143
	s_nop 0
	v_pk_mul_f32 v[84:85], v[80:81], v[94:95]
	s_nop 0
	v_pk_mul_f32 v[142:143], v[82:83], v[84:85]
	s_cbranch_vccnz .Lbrn_126
	s_lshl_b32 s22, s55, 8
	v_ashrrev_i32_e32 v215, 31, v214
	s_nop 1
	v_lshlrev_b64 v[84:85], 11, v[214:215]
	v_readlane_b32 s6, v253, 18
	v_readlane_b32 s7, v253, 19
	s_ashr_i32 s23, s22, 31
	v_mov_b32_e32 v87, s23
	v_lshl_add_u64 v[84:85], s[6:7], 0, v[84:85]
	v_or_b32_e32 v86, s22, v192
	v_lshl_add_u64 v[84:85], v[86:87], 1, v[84:85]
	v_cvt_pk_bf16_f32 v80, v132, v133
	v_cvt_pk_bf16_f32 v81, v134, v135
	v_cvt_pk_bf16_f32 v82, v140, v141
	v_cvt_pk_bf16_f32 v83, v142, v143
	s_nop 1
	global_store_dwordx4 v[84:85], v[80:83], off offset:256
.Lbrn_126:
	s_waitcnt vmcnt(10)
	v_lshlrev_b32_e32 v88, 16, v120
	v_and_b32_e32 v89, 0xffff0000, v120
	v_rcp_f32_e32 v88, v88
	v_rcp_f32_e32 v89, v89
	v_lshlrev_b32_e32 v80, 16, v116
	v_and_b32_e32 v81, 0xffff0000, v116
	v_lshlrev_b32_e32 v90, 16, v121
	v_pk_mul_f32 v[80:81], v[88:89], v[80:81]
	v_and_b32_e32 v91, 0xffff0000, v121
	v_lshlrev_b32_e32 v82, 16, v117
	v_and_b32_e32 v83, 0xffff0000, v117
	v_pk_mul_f32 v[116:117], v[76:77], v[80:81]
	v_rcp_f32_e32 v76, v90
	v_rcp_f32_e32 v77, v91
	v_lshlrev_b32_e32 v92, 16, v122
	v_and_b32_e32 v93, 0xffff0000, v122
	v_lshlrev_b32_e32 v84, 16, v118
	v_pk_mul_f32 v[80:81], v[76:77], v[82:83]
	v_and_b32_e32 v85, 0xffff0000, v118
	v_lshlrev_b32_e32 v86, 16, v119
	v_and_b32_e32 v87, 0xffff0000, v119
	v_pk_mul_f32 v[118:119], v[78:79], v[80:81]
	v_rcp_f32_e32 v76, v92
	v_rcp_f32_e32 v77, v93
	v_lshlrev_b32_e32 v94, 16, v123
	v_and_b32_e32 v95, 0xffff0000, v123
	s_and_b64 vcc, exec, s[38:39]
	v_pk_mul_f32 v[78:79], v[76:77], v[84:85]
	s_nop 0
	v_pk_mul_f32 v[120:121], v[72:73], v[78:79]
	v_rcp_f32_e32 v72, v94
	v_rcp_f32_e32 v73, v95
	s_nop 0
	v_pk_mul_f32 v[76:77], v[72:73], v[86:87]
	s_nop 0
	v_pk_mul_f32 v[122:123], v[74:75], v[76:77]
	s_cbranch_vccnz .Lbrn_128
	s_lshl_b32 s22, s55, 8
	v_ashrrev_i32_e32 v213, 31, v212
	s_nop 1
	v_lshlrev_b64 v[76:77], 11, v[212:213]
	v_readlane_b32 s6, v253, 18
	v_readlane_b32 s7, v253, 19
	s_ashr_i32 s23, s22, 31
	v_mov_b32_e32 v79, s23
	v_lshl_add_u64 v[76:77], s[6:7], 0, v[76:77]
	v_or_b32_e32 v78, s22, v192
	v_lshl_add_u64 v[76:77], v[78:79], 1, v[76:77]
	v_cvt_pk_bf16_f32 v72, v116, v117
	v_cvt_pk_bf16_f32 v73, v118, v119
	v_cvt_pk_bf16_f32 v74, v120, v121
	v_cvt_pk_bf16_f32 v75, v122, v123
	s_nop 1
	global_store_dwordx4 v[76:77], v[72:75], off offset:256
.Lbrn_128:
	s_waitcnt vmcnt(8)
	v_lshlrev_b32_e32 v80, 16, v104
	v_and_b32_e32 v81, 0xffff0000, v104
	v_rcp_f32_e32 v80, v80
	v_rcp_f32_e32 v81, v81
	v_lshlrev_b32_e32 v72, 16, v100
	v_and_b32_e32 v73, 0xffff0000, v100
	v_lshlrev_b32_e32 v82, 16, v105
	v_pk_mul_f32 v[72:73], v[80:81], v[72:73]
	v_and_b32_e32 v83, 0xffff0000, v105
	v_lshlrev_b32_e32 v74, 16, v101
	v_and_b32_e32 v75, 0xffff0000, v101
	v_pk_mul_f32 v[100:101], v[68:69], v[72:73]
	v_rcp_f32_e32 v68, v82
	v_rcp_f32_e32 v69, v83
	v_lshlrev_b32_e32 v84, 16, v106
	v_and_b32_e32 v85, 0xffff0000, v106
	v_lshlrev_b32_e32 v76, 16, v102
	v_pk_mul_f32 v[72:73], v[68:69], v[74:75]
	v_and_b32_e32 v77, 0xffff0000, v102
	v_lshlrev_b32_e32 v78, 16, v103
	v_and_b32_e32 v79, 0xffff0000, v103
	v_pk_mul_f32 v[102:103], v[70:71], v[72:73]
	v_rcp_f32_e32 v68, v84
	v_rcp_f32_e32 v69, v85
	v_lshlrev_b32_e32 v86, 16, v107
	v_and_b32_e32 v87, 0xffff0000, v107
	s_and_b64 vcc, exec, s[38:39]
	v_pk_mul_f32 v[70:71], v[68:69], v[76:77]
	s_nop 0
	v_pk_mul_f32 v[104:105], v[64:65], v[70:71]
	v_rcp_f32_e32 v64, v86
	v_rcp_f32_e32 v65, v87
	s_nop 0
	v_pk_mul_f32 v[68:69], v[64:65], v[78:79]
	s_nop 0
	v_pk_mul_f32 v[106:107], v[66:67], v[68:69]
	s_cbranch_vccnz .Lbrn_130
	s_lshl_b32 s22, s55, 8
	v_ashrrev_i32_e32 v211, 31, v210
	s_nop 1
	v_lshlrev_b64 v[68:69], 11, v[210:211]
	v_readlane_b32 s6, v253, 18
	v_readlane_b32 s7, v253, 19
	s_ashr_i32 s23, s22, 31
	v_mov_b32_e32 v71, s23
	v_lshl_add_u64 v[68:69], s[6:7], 0, v[68:69]
	v_or_b32_e32 v70, s22, v192
	v_lshl_add_u64 v[68:69], v[70:71], 1, v[68:69]
	v_cvt_pk_bf16_f32 v64, v100, v101
	v_cvt_pk_bf16_f32 v65, v102, v103
	v_cvt_pk_bf16_f32 v66, v104, v105
	v_cvt_pk_bf16_f32 v67, v106, v107
	s_nop 1
	global_store_dwordx4 v[68:69], v[64:67], off offset:256
.Lbrn_130:
	s_mov_b64 s[22:23], 0x101000
	s_nop 0
	v_lshl_add_u64 v[64:65], v[208:209], 0, s[22:23]
	v_add_co_u32_e32 v66, vcc, 0x101000, v208
	v_lshl_add_u64 v[64:65], v[64:65], 0, s[88:89]
	s_nop 0
	v_addc_co_u32_e32 v67, vcc, 0, v209, vcc
	s_mov_b64 s[22:23], 0x121000
	global_load_dwordx4 v[88:91], v[66:67], off
	global_load_dwordx4 v[92:95], v[64:65], off
	v_lshl_add_u64 v[64:65], v[208:209], 0, s[22:23]
	v_add_co_u32_e32 v66, vcc, 0x121000, v208
	v_lshl_add_u64 v[64:65], v[64:65], 0, s[88:89]
	s_nop 0
	v_addc_co_u32_e32 v67, vcc, 0, v209, vcc
	s_mov_b64 s[22:23], 0x141000
	global_load_dwordx4 v[80:83], v[66:67], off
	global_load_dwordx4 v[84:87], v[64:65], off
	v_lshl_add_u64 v[64:65], v[208:209], 0, s[22:23]
	v_add_co_u32_e32 v66, vcc, 0x141000, v208
	v_lshl_add_u64 v[64:65], v[64:65], 0, s[88:89]
	s_nop 0
	v_addc_co_u32_e32 v67, vcc, 0, v209, vcc
	s_mov_b64 s[22:23], 0x161000
	global_load_dwordx4 v[72:75], v[66:67], off
	global_load_dwordx4 v[76:79], v[64:65], off
	v_lshl_add_u64 v[68:69], v[208:209], 0, s[22:23]
	v_add_co_u32_e32 v64, vcc, 0x161000, v208
	v_lshl_add_u64 v[68:69], v[68:69], 0, s[88:89]
	s_nop 0
	v_addc_co_u32_e32 v65, vcc, 0, v209, vcc
	global_load_dwordx4 v[64:67], v[64:65], off
	s_waitcnt vmcnt(13)
	v_lshlrev_b32_e32 v207, 16, v144
	global_load_dwordx4 v[68:71], v[68:69], off
	v_and_b32_e32 v209, 0xffff0000, v144
	v_rcp_f32_e32 v208, v207
	v_rcp_f32_e32 v209, v209
	v_lshlrev_b32_e32 v210, 16, v145
	v_and_b32_e32 v211, 0xffff0000, v145
	v_lshlrev_b32_e32 v144, 16, v148
	v_and_b32_e32 v145, 0xffff0000, v148
	v_pk_mul_f32 v[144:145], v[208:209], v[144:145]
	v_lshlrev_b32_e32 v212, 16, v146
	v_pk_mul_f32 v[60:61], v[60:61], v[144:145]
	v_rcp_f32_e32 v144, v210
	v_rcp_f32_e32 v145, v211
	v_and_b32_e32 v213, 0xffff0000, v146
	v_lshlrev_b32_e32 v214, 16, v147
	v_and_b32_e32 v215, 0xffff0000, v147
	v_lshlrev_b32_e32 v146, 16, v149
	v_and_b32_e32 v147, 0xffff0000, v149
	v_pk_mul_f32 v[146:147], v[144:145], v[146:147]
	v_lshlrev_b32_e32 v148, 16, v150
	v_pk_mul_f32 v[62:63], v[62:63], v[146:147]
	v_rcp_f32_e32 v144, v212
	v_rcp_f32_e32 v145, v213
	v_and_b32_e32 v149, 0xffff0000, v150
	v_lshlrev_b32_e32 v150, 16, v151
	v_and_b32_e32 v151, 0xffff0000, v151
	v_pk_mul_f32 v[146:147], v[144:145], v[148:149]
	s_and_b64 vcc, exec, s[38:39]
	v_pk_mul_f32 v[56:57], v[56:57], v[146:147]
	v_rcp_f32_e32 v144, v214
	v_rcp_f32_e32 v145, v215
	s_nop 0
	v_pk_mul_f32 v[146:147], v[144:145], v[150:151]
	s_nop 0
	v_pk_mul_f32 v[58:59], v[58:59], v[146:147]
	v_lshl_add_u32 v144, s52, 8, v247
	s_cbranch_vccnz .Lbrn_132
	v_ashrrev_i32_e32 v145, 31, v144
	s_nop 1
	v_lshlrev_b64 v[150:151], 11, v[144:145]
	v_readlane_b32 s6, v253, 18
	v_readlane_b32 s7, v253, 19
	v_ashrrev_i32_e32 v207, 31, v206
	v_cvt_pk_bf16_f32 v146, v60, v61
	v_cvt_pk_bf16_f32 v147, v62, v63
	v_cvt_pk_bf16_f32 v148, v56, v57
	v_cvt_pk_bf16_f32 v149, v58, v59
	s_nop 0
	v_lshl_add_u64 v[150:151], s[6:7], 0, v[150:151]
	v_lshl_add_u64 v[150:151], v[206:207], 1, v[150:151]
	s_nop 1
	global_store_dwordx4 v[150:151], v[146:149], off
.Lbrn_132:
	s_waitcnt vmcnt(12)
	v_lshlrev_b32_e32 v145, 16, v128
	s_nop 0
	v_and_b32_e32 v147, 0xffff0000, v128
	v_rcp_f32_e32 v146, v145
	v_rcp_f32_e32 v147, v147
	v_lshlrev_b32_e32 v148, 16, v129
	v_and_b32_e32 v149, 0xffff0000, v129
	v_lshlrev_b32_e32 v128, 16, v136
	v_and_b32_e32 v129, 0xffff0000, v136
	v_pk_mul_f32 v[128:129], v[146:147], v[128:129]
	v_lshlrev_b32_e32 v150, 16, v130
	v_pk_mul_f32 v[52:53], v[52:53], v[128:129]
	v_rcp_f32_e32 v128, v148
	v_rcp_f32_e32 v129, v149
	v_and_b32_e32 v151, 0xffff0000, v130
	v_lshlrev_b32_e32 v207, 16, v131
	v_and_b32_e32 v208, 0xffff0000, v131
	v_lshlrev_b32_e32 v130, 16, v137
	v_and_b32_e32 v131, 0xffff0000, v137
	v_pk_mul_f32 v[130:131], v[128:129], v[130:131]
	v_lshlrev_b32_e32 v136, 16, v138
	v_pk_mul_f32 v[54:55], v[54:55], v[130:131]
	v_rcp_f32_e32 v128, v150
	v_rcp_f32_e32 v129, v151
	v_and_b32_e32 v137, 0xffff0000, v138
	v_lshlrev_b32_e32 v138, 16, v139
	v_and_b32_e32 v139, 0xffff0000, v139
	v_pk_mul_f32 v[130:131], v[128:129], v[136:137]
	s_and_b64 vcc, exec, s[38:39]
	v_pk_mul_f32 v[48:49], v[48:49], v[130:131]
	v_rcp_f32_e32 v128, v207
	v_rcp_f32_e32 v129, v208
	s_nop 0
	v_pk_mul_f32 v[130:131], v[128:129], v[138:139]
	s_nop 0
	v_pk_mul_f32 v[50:51], v[50:51], v[130:131]
	v_lshl_add_u32 v128, s52, 8, v248
	s_cbranch_vccnz .Lbrn_134
	v_ashrrev_i32_e32 v129, 31, v128
	s_nop 1
	v_lshlrev_b64 v[130:131], 11, v[128:129]
	v_readlane_b32 s6, v253, 18
	v_readlane_b32 s7, v253, 19
	v_ashrrev_i32_e32 v207, 31, v206
	v_cvt_pk_bf16_f32 v136, v52, v53
	v_cvt_pk_bf16_f32 v137, v54, v55
	v_cvt_pk_bf16_f32 v138, v48, v49
	v_cvt_pk_bf16_f32 v139, v50, v51
	s_nop 0
	v_lshl_add_u64 v[130:131], s[6:7], 0, v[130:131]
	v_lshl_add_u64 v[130:131], v[206:207], 1, v[130:131]
	s_nop 1
	global_store_dwordx4 v[130:131], v[136:139], off
.Lbrn_134:
	s_waitcnt vmcnt(10)
	v_lshlrev_b32_e32 v129, 16, v112
	v_and_b32_e32 v131, 0xffff0000, v112
	v_rcp_f32_e32 v130, v129
	v_rcp_f32_e32 v131, v131
	v_lshlrev_b32_e32 v136, 16, v113
	v_and_b32_e32 v137, 0xffff0000, v113
	v_lshlrev_b32_e32 v112, 16, v124
	v_and_b32_e32 v113, 0xffff0000, v124
	v_pk_mul_f32 v[112:113], v[130:131], v[112:113]
	v_lshlrev_b32_e32 v138, 16, v114
	v_pk_mul_f32 v[44:45], v[44:45], v[112:113]
	v_rcp_f32_e32 v112, v136
	v_rcp_f32_e32 v113, v137
	v_and_b32_e32 v139, 0xffff0000, v114
	v_lshlrev_b32_e32 v145, 16, v115
	v_and_b32_e32 v146, 0xffff0000, v115
	v_lshlrev_b32_e32 v114, 16, v125
	v_and_b32_e32 v115, 0xffff0000, v125
	v_pk_mul_f32 v[114:115], v[112:113], v[114:115]
	v_lshlrev_b32_e32 v124, 16, v126
	v_pk_mul_f32 v[46:47], v[46:47], v[114:115]
	v_rcp_f32_e32 v112, v138
	v_rcp_f32_e32 v113, v139
	v_and_b32_e32 v125, 0xffff0000, v126
	v_lshlrev_b32_e32 v126, 16, v127
	v_and_b32_e32 v127, 0xffff0000, v127
	v_pk_mul_f32 v[114:115], v[112:113], v[124:125]
	s_and_b64 vcc, exec, s[38:39]
	v_pk_mul_f32 v[40:41], v[40:41], v[114:115]
	v_rcp_f32_e32 v112, v145
	v_rcp_f32_e32 v113, v146
	s_nop 0
	v_pk_mul_f32 v[114:115], v[112:113], v[126:127]
	s_nop 0
	v_pk_mul_f32 v[42:43], v[42:43], v[114:115]
	v_lshl_add_u32 v112, s52, 8, v249
	s_cbranch_vccnz .Lbrn_136
	v_ashrrev_i32_e32 v113, 31, v112
	s_nop 1
	v_lshlrev_b64 v[114:115], 11, v[112:113]
	v_readlane_b32 s6, v253, 18
	v_readlane_b32 s7, v253, 19
	v_ashrrev_i32_e32 v207, 31, v206
	v_cvt_pk_bf16_f32 v124, v44, v45
	v_cvt_pk_bf16_f32 v125, v46, v47
	v_cvt_pk_bf16_f32 v126, v40, v41
	v_cvt_pk_bf16_f32 v127, v42, v43
	s_nop 0
	v_lshl_add_u64 v[114:115], s[6:7], 0, v[114:115]
	v_lshl_add_u64 v[114:115], v[206:207], 1, v[114:115]
	s_nop 1
	global_store_dwordx4 v[114:115], v[124:127], off
.Lbrn_136:
	s_waitcnt vmcnt(8)
	v_lshlrev_b32_e32 v113, 16, v96
	v_and_b32_e32 v115, 0xffff0000, v96
	v_rcp_f32_e32 v114, v113
	v_rcp_f32_e32 v115, v115
	v_lshlrev_b32_e32 v124, 16, v97
	v_and_b32_e32 v125, 0xffff0000, v97
	v_lshlrev_b32_e32 v96, 16, v108
	v_and_b32_e32 v97, 0xffff0000, v108
	v_pk_mul_f32 v[96:97], v[114:115], v[96:97]
	v_lshlrev_b32_e32 v126, 16, v98
	v_pk_mul_f32 v[36:37], v[36:37], v[96:97]
	v_rcp_f32_e32 v96, v124
	v_rcp_f32_e32 v97, v125
	v_and_b32_e32 v127, 0xffff0000, v98
	v_lshlrev_b32_e32 v129, 16, v99
	v_and_b32_e32 v130, 0xffff0000, v99
	v_lshlrev_b32_e32 v98, 16, v109
	v_and_b32_e32 v99, 0xffff0000, v109
	v_pk_mul_f32 v[98:99], v[96:97], v[98:99]
	v_lshlrev_b32_e32 v108, 16, v110
	v_pk_mul_f32 v[38:39], v[38:39], v[98:99]
	v_rcp_f32_e32 v96, v126
	v_rcp_f32_e32 v97, v127
	v_and_b32_e32 v109, 0xffff0000, v110
	v_lshlrev_b32_e32 v110, 16, v111
	v_and_b32_e32 v111, 0xffff0000, v111
	v_pk_mul_f32 v[98:99], v[96:97], v[108:109]
	s_and_b64 vcc, exec, s[38:39]
	v_pk_mul_f32 v[32:33], v[32:33], v[98:99]
	v_rcp_f32_e32 v96, v129
	v_rcp_f32_e32 v97, v130
	s_nop 0
	v_pk_mul_f32 v[98:99], v[96:97], v[110:111]
	s_nop 0
	v_pk_mul_f32 v[34:35], v[34:35], v[98:99]
	v_lshl_add_u32 v96, s52, 8, v250
	s_cbranch_vccnz .Lbrn_138
	v_ashrrev_i32_e32 v97, 31, v96
	s_nop 1
	v_lshlrev_b64 v[98:99], 11, v[96:97]
	v_readlane_b32 s6, v253, 18
	v_readlane_b32 s7, v253, 19
	v_ashrrev_i32_e32 v207, 31, v206
	v_cvt_pk_bf16_f32 v108, v36, v37
	v_cvt_pk_bf16_f32 v109, v38, v39
	v_cvt_pk_bf16_f32 v110, v32, v33
	v_cvt_pk_bf16_f32 v111, v34, v35
	s_nop 0
	v_lshl_add_u64 v[98:99], s[6:7], 0, v[98:99]
	v_lshl_add_u64 v[98:99], v[206:207], 1, v[98:99]
	s_nop 1
	global_store_dwordx4 v[98:99], v[108:111], off
.Lbrn_138:
	s_waitcnt vmcnt(6)
	v_lshlrev_b32_e32 v97, 16, v88
	v_and_b32_e32 v99, 0xffff0000, v88
	v_rcp_f32_e32 v98, v97
	v_rcp_f32_e32 v99, v99
	v_lshlrev_b32_e32 v108, 16, v89
	v_and_b32_e32 v109, 0xffff0000, v89
	v_lshlrev_b32_e32 v88, 16, v92
	v_and_b32_e32 v89, 0xffff0000, v92
	v_pk_mul_f32 v[88:89], v[98:99], v[88:89]
	v_lshlrev_b32_e32 v110, 16, v90
	v_pk_mul_f32 v[28:29], v[28:29], v[88:89]
	v_rcp_f32_e32 v88, v108
	v_rcp_f32_e32 v89, v109
	v_and_b32_e32 v111, 0xffff0000, v90
	v_lshlrev_b32_e32 v113, 16, v91
	v_and_b32_e32 v114, 0xffff0000, v91
	v_lshlrev_b32_e32 v90, 16, v93
	v_and_b32_e32 v91, 0xffff0000, v93
	v_pk_mul_f32 v[90:91], v[88:89], v[90:91]
	v_lshlrev_b32_e32 v92, 16, v94
	v_pk_mul_f32 v[30:31], v[30:31], v[90:91]
	v_rcp_f32_e32 v88, v110
	v_rcp_f32_e32 v89, v111
	v_and_b32_e32 v93, 0xffff0000, v94
	v_lshlrev_b32_e32 v94, 16, v95
	v_and_b32_e32 v95, 0xffff0000, v95
	v_pk_mul_f32 v[90:91], v[88:89], v[92:93]
	s_and_b64 vcc, exec, s[38:39]
	v_pk_mul_f32 v[24:25], v[24:25], v[90:91]
	v_rcp_f32_e32 v88, v113
	v_rcp_f32_e32 v89, v114
	s_nop 0
	v_pk_mul_f32 v[90:91], v[88:89], v[94:95]
	s_nop 0
	v_pk_mul_f32 v[26:27], v[26:27], v[90:91]
	s_cbranch_vccnz .Lbrn_140
	s_lshl_b32 s22, s55, 8
	v_ashrrev_i32_e32 v145, 31, v144
	s_nop 1
	v_lshlrev_b64 v[92:93], 11, v[144:145]
	v_readlane_b32 s6, v253, 18
	v_readlane_b32 s7, v253, 19
	s_ashr_i32 s23, s22, 31
	v_mov_b32_e32 v95, s23
	v_lshl_add_u64 v[92:93], s[6:7], 0, v[92:93]
	v_or_b32_e32 v94, s22, v192
	v_lshl_add_u64 v[92:93], v[94:95], 1, v[92:93]
	v_cvt_pk_bf16_f32 v88, v28, v29
	v_cvt_pk_bf16_f32 v89, v30, v31
	v_cvt_pk_bf16_f32 v90, v24, v25
	v_cvt_pk_bf16_f32 v91, v26, v27
	s_nop 1
	global_store_dwordx4 v[92:93], v[88:91], off offset:256
.Lbrn_140:
	s_waitcnt vmcnt(4)
	s_nop 1
	v_lshlrev_b32_e32 v88, 16, v80
	v_and_b32_e32 v89, 0xffff0000, v80
	v_rcp_f32_e32 v88, v88
	v_rcp_f32_e32 v89, v89
	v_lshlrev_b32_e32 v90, 16, v81
	v_and_b32_e32 v91, 0xffff0000, v81
	v_lshlrev_b32_e32 v80, 16, v84
	v_and_b32_e32 v81, 0xffff0000, v84
	v_pk_mul_f32 v[80:81], v[88:89], v[80:81]
	v_lshlrev_b32_e32 v92, 16, v82
	v_pk_mul_f32 v[20:21], v[20:21], v[80:81]
	v_rcp_f32_e32 v80, v90
	v_rcp_f32_e32 v81, v91
	v_and_b32_e32 v93, 0xffff0000, v82
	v_lshlrev_b32_e32 v94, 16, v83
	v_and_b32_e32 v95, 0xffff0000, v83
	v_lshlrev_b32_e32 v82, 16, v85
	v_and_b32_e32 v83, 0xffff0000, v85
	v_pk_mul_f32 v[82:83], v[80:81], v[82:83]
	v_lshlrev_b32_e32 v84, 16, v86
	v_pk_mul_f32 v[22:23], v[22:23], v[82:83]
	v_rcp_f32_e32 v80, v92
	v_rcp_f32_e32 v81, v93
	v_and_b32_e32 v85, 0xffff0000, v86
	v_lshlrev_b32_e32 v86, 16, v87
	v_and_b32_e32 v87, 0xffff0000, v87
	v_pk_mul_f32 v[82:83], v[80:81], v[84:85]
	s_and_b64 vcc, exec, s[38:39]
	v_pk_mul_f32 v[16:17], v[16:17], v[82:83]
	v_rcp_f32_e32 v80, v94
	v_rcp_f32_e32 v81, v95
	s_nop 0
	v_pk_mul_f32 v[82:83], v[80:81], v[86:87]
	s_nop 0
	v_pk_mul_f32 v[18:19], v[18:19], v[82:83]
	s_cbranch_vccnz .Lbrn_142
	s_lshl_b32 s22, s55, 8
	v_ashrrev_i32_e32 v129, 31, v128
	s_nop 1
	v_lshlrev_b64 v[84:85], 11, v[128:129]
	v_readlane_b32 s6, v253, 18
	v_readlane_b32 s7, v253, 19
	s_ashr_i32 s23, s22, 31
	v_mov_b32_e32 v87, s23
	v_lshl_add_u64 v[84:85], s[6:7], 0, v[84:85]
	v_or_b32_e32 v86, s22, v192
	v_lshl_add_u64 v[84:85], v[86:87], 1, v[84:85]
	v_cvt_pk_bf16_f32 v80, v20, v21
	v_cvt_pk_bf16_f32 v81, v22, v23
	v_cvt_pk_bf16_f32 v82, v16, v17
	v_cvt_pk_bf16_f32 v83, v18, v19
	s_nop 1
	global_store_dwordx4 v[84:85], v[80:83], off offset:256
.Lbrn_142:
	s_waitcnt vmcnt(2)
	s_nop 1
	v_lshlrev_b32_e32 v80, 16, v72
	v_and_b32_e32 v81, 0xffff0000, v72
	v_rcp_f32_e32 v80, v80
	v_rcp_f32_e32 v81, v81
	v_lshlrev_b32_e32 v82, 16, v73
	v_and_b32_e32 v83, 0xffff0000, v73
	v_lshlrev_b32_e32 v72, 16, v76
	v_and_b32_e32 v73, 0xffff0000, v76
	v_pk_mul_f32 v[72:73], v[80:81], v[72:73]
	v_lshlrev_b32_e32 v84, 16, v74
	v_pk_mul_f32 v[12:13], v[12:13], v[72:73]
	v_rcp_f32_e32 v72, v82
	v_rcp_f32_e32 v73, v83
	v_and_b32_e32 v85, 0xffff0000, v74
	v_lshlrev_b32_e32 v86, 16, v75
	v_and_b32_e32 v87, 0xffff0000, v75
	v_lshlrev_b32_e32 v74, 16, v77
	v_and_b32_e32 v75, 0xffff0000, v77
	v_pk_mul_f32 v[74:75], v[72:73], v[74:75]
	v_lshlrev_b32_e32 v76, 16, v78
	v_pk_mul_f32 v[14:15], v[14:15], v[74:75]
	v_rcp_f32_e32 v72, v84
	v_rcp_f32_e32 v73, v85
	v_and_b32_e32 v77, 0xffff0000, v78
	v_lshlrev_b32_e32 v78, 16, v79
	v_and_b32_e32 v79, 0xffff0000, v79
	v_pk_mul_f32 v[74:75], v[72:73], v[76:77]
	s_and_b64 vcc, exec, s[38:39]
	v_pk_mul_f32 v[4:5], v[4:5], v[74:75]
	v_rcp_f32_e32 v72, v86
	v_rcp_f32_e32 v73, v87
	s_nop 0
	v_pk_mul_f32 v[74:75], v[72:73], v[78:79]
	s_nop 0
	v_pk_mul_f32 v[6:7], v[6:7], v[74:75]
	s_cbranch_vccnz .Lbrn_144
	s_lshl_b32 s22, s55, 8
	v_ashrrev_i32_e32 v113, 31, v112
	s_nop 1
	v_lshlrev_b64 v[76:77], 11, v[112:113]
	v_readlane_b32 s6, v253, 18
	v_readlane_b32 s7, v253, 19
	s_ashr_i32 s23, s22, 31
	v_mov_b32_e32 v79, s23
	v_lshl_add_u64 v[76:77], s[6:7], 0, v[76:77]
	v_or_b32_e32 v78, s22, v192
	v_lshl_add_u64 v[76:77], v[78:79], 1, v[76:77]
	v_cvt_pk_bf16_f32 v72, v12, v13
	v_cvt_pk_bf16_f32 v73, v14, v15
	v_cvt_pk_bf16_f32 v74, v4, v5
	v_cvt_pk_bf16_f32 v75, v6, v7
	s_nop 1
	global_store_dwordx4 v[76:77], v[72:75], off offset:256
.Lbrn_144:
	s_waitcnt vmcnt(1)
	s_nop 1
	v_lshlrev_b32_e32 v72, 16, v64
	v_and_b32_e32 v73, 0xffff0000, v64
	v_rcp_f32_e32 v72, v72
	v_rcp_f32_e32 v73, v73
	v_lshlrev_b32_e32 v74, 16, v65
	v_and_b32_e32 v75, 0xffff0000, v65
	s_waitcnt vmcnt(0)
	v_lshlrev_b32_e32 v64, 16, v68
	v_and_b32_e32 v65, 0xffff0000, v68
	v_pk_mul_f32 v[64:65], v[72:73], v[64:65]
	v_lshlrev_b32_e32 v76, 16, v66
	v_pk_mul_f32 v[8:9], v[8:9], v[64:65]
	v_rcp_f32_e32 v64, v74
	v_rcp_f32_e32 v65, v75
	v_and_b32_e32 v77, 0xffff0000, v66
	v_lshlrev_b32_e32 v78, 16, v67
	v_and_b32_e32 v79, 0xffff0000, v67
	v_lshlrev_b32_e32 v66, 16, v69
	v_and_b32_e32 v67, 0xffff0000, v69
	v_pk_mul_f32 v[66:67], v[64:65], v[66:67]
	v_lshlrev_b32_e32 v68, 16, v70
	v_pk_mul_f32 v[10:11], v[10:11], v[66:67]
	v_rcp_f32_e32 v64, v76
	v_rcp_f32_e32 v65, v77
	v_and_b32_e32 v69, 0xffff0000, v70
	v_lshlrev_b32_e32 v70, 16, v71
	v_and_b32_e32 v71, 0xffff0000, v71
	v_pk_mul_f32 v[66:67], v[64:65], v[68:69]
	s_and_b64 vcc, exec, s[38:39]
	v_pk_mul_f32 v[0:1], v[0:1], v[66:67]
	v_rcp_f32_e32 v64, v78
	v_rcp_f32_e32 v65, v79
	s_nop 0
	v_pk_mul_f32 v[66:67], v[64:65], v[70:71]
	s_nop 0
	v_pk_mul_f32 v[2:3], v[2:3], v[66:67]
	s_cbranch_vccnz .LBB0_107
	s_lshl_b32 s22, s55, 8
	v_ashrrev_i32_e32 v97, 31, v96
	s_nop 1
	v_lshlrev_b64 v[68:69], 11, v[96:97]
	v_readlane_b32 s6, v253, 18
	v_readlane_b32 s7, v253, 19
	s_ashr_i32 s23, s22, 31
	v_mov_b32_e32 v71, s23
	v_lshl_add_u64 v[68:69], s[6:7], 0, v[68:69]
	v_or_b32_e32 v70, s22, v192
	v_lshl_add_u64 v[68:69], v[70:71], 1, v[68:69]
	v_cvt_pk_bf16_f32 v64, v8, v9
	v_cvt_pk_bf16_f32 v65, v10, v11
	v_cvt_pk_bf16_f32 v66, v0, v1
	v_cvt_pk_bf16_f32 v67, v2, v3
	s_nop 1
	global_store_dwordx4 v[68:69], v[64:67], off offset:256
	s_branch .LBB0_107
